# v34 + mLSTM state publish packs two f32 per v_cvt_pk and stores halves with ds_write_b16 / ds_write_b16_d16_hi
# speedup vs baseline: 1.0046x; 1.0020x over previous
; #define LAS __attribute__((address_space(3)))
; DI unsigned pk2(float lo, float hi) { f32x2 v = {lo, hi}; bf16x2_t b = __builtin_convertvector(v, bf16x2_t); return __builtin_bit_cast(unsigned, b); }
; DI void mlstm_phase(LAS unsigned char* lds, const bf16_t* proj, const float* gates, bf16_t* Hfw, bf16_t* Hbw, int G, int bid) {
;     ...
;             if (nown > 0) {
; #pragma unroll
;                 for (int dt = 0; dt < 5; ++dt)
; #pragma unroll
;                     for (int i = 0; i < 4; ++i)
;                         *(LAS bf16_t*)(Cs + (16 * dt + 4 * fq + i) * MQ_STRIDE + (16 * wid + fr) * 2) = (bf16_t)(pk2(Creg[0][dt][i], 0.f) & 0xffffu);
;                 if (nown == 2) {
; #pragma unroll
;                     for (int dt = 0; dt < 5; ++dt)
; #pragma unroll
;                         for (int i = 0; i < 4; ++i)
;                             *(LAS bf16_t*)(Cs + (16 * dt + 4 * fq + i) * MQ_STRIDE + (16 * (wid + 6) + fr) * 2) = (bf16_t)(pk2(Creg[1][dt][i], 0.f) & 0xffffu);
;                 }
;             }
.LBB0_873:
	s_waitcnt lgkmcnt(0)
	s_barrier
	s_and_b64 vcc, exec, s[94:95]
	s_cbranch_vccnz .LBB0_835
	v_cvt_pk_bf16_f32 v0, v80, v81
	ds_write_b16 v199, v0
	ds_write_b16_d16_hi v199, v0 offset:272
	v_cvt_pk_bf16_f32 v0, v82, v83
	ds_write_b16 v199, v0 offset:544
	ds_write_b16_d16_hi v199, v0 offset:816
	v_cvt_pk_bf16_f32 v0, v76, v77
	ds_write_b16 v199, v0 offset:4352
	ds_write_b16_d16_hi v199, v0 offset:4624
	v_cvt_pk_bf16_f32 v0, v78, v79
	ds_write_b16 v199, v0 offset:4896
	ds_write_b16_d16_hi v199, v0 offset:5168
	v_cvt_pk_bf16_f32 v0, v72, v73
	ds_write_b16 v199, v0 offset:8704
	ds_write_b16_d16_hi v199, v0 offset:8976
	v_cvt_pk_bf16_f32 v0, v74, v75
	ds_write_b16 v199, v0 offset:9248
	ds_write_b16_d16_hi v199, v0 offset:9520
	v_cvt_pk_bf16_f32 v0, v68, v69
	ds_write_b16 v199, v0 offset:13056
	ds_write_b16_d16_hi v199, v0 offset:13328
	v_cvt_pk_bf16_f32 v0, v70, v71
	ds_write_b16 v199, v0 offset:13600
	ds_write_b16_d16_hi v199, v0 offset:13872
	v_cvt_pk_bf16_f32 v0, v64, v65
	ds_write_b16 v199, v0 offset:17408
	ds_write_b16_d16_hi v199, v0 offset:17680
	v_cvt_pk_bf16_f32 v0, v66, s0
	ds_write_b16 v199, v0 offset:17952
	v_cvt_pk_bf16_f32 v0, v67, s0
	s_and_b64 vcc, exec, s[92:93]
	ds_write_b16 v199, v0 offset:18224
	s_cbranch_vccnz .LBB0_835
	v_cvt_pk_bf16_f32 v0, v44, v45
	ds_write_b16 v200, v0
	ds_write_b16_d16_hi v200, v0 offset:272
	v_cvt_pk_bf16_f32 v0, v46, v47
	ds_write_b16 v200, v0 offset:544
	ds_write_b16_d16_hi v200, v0 offset:816
	v_cvt_pk_bf16_f32 v0, v48, v49
	ds_write_b16 v200, v0 offset:4352
	ds_write_b16_d16_hi v200, v0 offset:4624
	v_cvt_pk_bf16_f32 v0, v50, v51
	ds_write_b16 v200, v0 offset:4896
	ds_write_b16_d16_hi v200, v0 offset:5168
	v_cvt_pk_bf16_f32 v0, v52, v53
	ds_write_b16 v200, v0 offset:8704
	ds_write_b16_d16_hi v200, v0 offset:8976
	v_cvt_pk_bf16_f32 v0, v54, v55
	ds_write_b16 v200, v0 offset:9248
	ds_write_b16_d16_hi v200, v0 offset:9520
	v_cvt_pk_bf16_f32 v0, v56, v57
	ds_write_b16 v200, v0 offset:13056
	ds_write_b16_d16_hi v200, v0 offset:13328
	v_cvt_pk_bf16_f32 v0, v58, v59
	ds_write_b16 v200, v0 offset:13600
	ds_write_b16_d16_hi v200, v0 offset:13872
	v_cvt_pk_bf16_f32 v0, v60, v61
	ds_write_b16 v200, v0 offset:17408
	ds_write_b16_d16_hi v200, v0 offset:17680
	v_cvt_pk_bf16_f32 v0, v62, v63
	ds_write_b16 v200, v0 offset:17952
	ds_write_b16_d16_hi v200, v0 offset:18224
	s_branch .LBB0_835
